# attention B/C: lazy O-rescale when no row max moved, fewer softmax VALU ops, Q-fragment prologue loads issued together
# speedup vs baseline: 1.0374x; 1.0132x over previous
; template <int DQK, int DV, int MODE> ...
;     ...
;   bf16_t* Qs = (bf16_t*)(smem + ATT_Q_OFF) + (w * 2 * NKS) * 512 + lane * 8;
; #pragma unroll
;   for (int qi = 0; qi < 2; ++qi)
; #pragma unroll
;     for (int ks = 0; ks < NKS; ++ks)
;       *(bf16x8*)(Qs + (qi * NKS + ks) * 512) = *(const bf16x8*)(Qp + (unsigned)((w * 32 + qi * 16 + fr) * qrs + ks * 32 + fq * 8));
; #pragma unroll
;   for (int qi = 0; qi < 2; ++qi) {
;     mrow[qi] = -1e30f; lrow[qi] = 0.f;
; #pragma unroll
;     for (int dt = 0; dt < NDT; ++dt) O[qi][dt] = (f32x4){0.f, 0.f, 0.f, 0.f};
;   }
;   int wkb, wke;
;   if (MODE == 0) { wkb = max(kt_begin, w >> 1); wke = (w * 32 + 159) / 64 + 1; }
;   else { wkb = 0; wke = (qpos0 + w * 32 + 31) / 64 + 1; }
;   u32x4 rk[NKC], rv[NVC];
;   auto gload = [&](int kt) {
; #pragma unroll
;     for (int i = 0; i < NKC; ++i) { const int c = tid + 256 * i, key = c / KCH, part = c % KCH; rk[i] = *(const u32x4*)(Kp + (unsigned)((kt * 64 + key) * krs + part * 8)); }
;     if (MODE == 0) {
; #pragma unroll
;       for (int i = 0; i < NVC; ++i) { const int c = tid + 256 * i, key = c >> 3, part = c & 7; rv[i] = *(const u32x4*)(Vp + (unsigned)((kt * 64 + key) * vrs + part * 8)); }
;     } else {
; #pragma unroll
;       for (int i = 0; i < NVC; ++i) { const int c = tid + 256 * i, dv = c >> 3, kc = c & 7; rv[i] = *(const u32x4*)(Vp + (unsigned)(dv * vrs + kt * 64 + kc * 8)); }
;     }
;   };
;   auto sstore = [&]() {
; #pragma unroll
;     for (int i = 0; i < NKC; ++i) { const int c = tid + 256 * i, key = c / KCH, part = c % KCH; *(u32x4*)(Ks + key * KST + part * 8) = rk[i]; }
;     if (MODE == 0) {
; #pragma unroll
;       for (int i = 0; i < NVC; ++i) {
;         const int c = tid + 256 * i, key = c >> 3, part = c & 7;
;         const int pos = (key & 32) + ((key >> 2) & 3) * 8 + ((key >> 4) & 1) * 4 + (key & 3);
; #pragma unroll
;         for (int e = 0; e < 8; ++e) Vt[(part * 8 + e) * VTS + pos] = (bf16_t)(rv[i][e >> 1] >> ((e & 1) * 16));
;       }
;     } else {
; #pragma unroll
;       for (int i = 0; i < NVC; ++i) {
;         const int c = tid + 256 * i, dv = c >> 3, kc = c & 7;
;         const int pos0 = (kc >> 2) * 32 + ((kc & 1) * 2) * 8 + ((kc >> 1) & 1) * 4;
;         *(u32x2*)(Vt + dv * VTS + pos0) = (u32x2){rv[i].x, rv[i].y};
;         *(u32x2*)(Vt + dv * VTS + pos0 + 8) = (u32x2){rv[i].z, rv[i].w};
;       }
;     }
;   };
;   gload(kt_begin);
.LBB0_531:
	s_or_b64 exec, exec, s[0:1]
	s_lshl_b32 s0, s18, 6
	s_and_b32 s2, s0, 0xffffff80
	s_sub_i32 s3, 0x1f80, s2
	v_readlane_b32 s0, v252, 12
	s_add_i32 s74, s3, s0
	s_sub_i32 s0, 0x1fc0, s2
	s_and_b32 s22, s18, 1
	s_lshr_b32 s23, s0, 6
	s_lshl_b64 s[0:1], s[74:75], 11
	v_readlane_b32 s4, v252, 23
	s_add_u32 s0, s4, s0
	v_readlane_b32 s4, v252, 24
	s_addc_u32 s1, s4, s1
	s_lshl_b32 s4, s22, 7
	s_add_u32 s0, s0, s4
	s_addc_u32 s1, s1, 0
	s_waitcnt vmcnt(0)
	v_lshl_add_u64 v[90:91], v[140:141], 1, s[0:1]
	v_lshl_add_u64 v[98:99], v[142:143], 1, s[0:1]
	v_lshl_add_u64 v[102:103], v[144:145], 1, s[0:1]
	global_load_dwordx4 v[94:97], v[90:91], off offset:64
	global_load_dwordx4 v[90:93], v[90:91], off
	global_load_dwordx4 v[98:101], v[98:99], off
	global_load_dwordx4 v[102:105], v[102:103], off
	v_readlane_b32 s5, v252, 41
	s_add_u32 s18, s5, s4
	v_readlane_b32 s4, v252, 42
	s_addc_u32 s19, s4, 0
	v_add_u32_e32 v226, s3, v212
	v_ashrrev_i32_e32 v0, 31, v226
	v_lshrrev_b32_e32 v0, 26, v0
	v_mov_b32_e32 v12, v1
	v_mov_b32_e32 v13, v1
	v_add3_u32 v0, v0, v226, 31
	v_mov_b32_e32 v10, v1
	v_mov_b32_e32 v11, v1
	v_mov_b64_e32 v[24:25], v[12:13]
	v_mov_b64_e32 v[36:37], v[12:13]
	v_mov_b64_e32 v[40:41], v[12:13]
	v_mov_b64_e32 v[44:45], v[12:13]
	v_mov_b64_e32 v[48:49], v[12:13]
	v_mov_b64_e32 v[52:53], v[12:13]
	v_mov_b64_e32 v[56:57], v[12:13]
	v_mov_b64_e32 v[60:61], v[12:13]
	v_mov_b64_e32 v[64:65], v[12:13]
	v_mov_b64_e32 v[68:69], v[12:13]
	v_mov_b64_e32 v[72:73], v[12:13]
	v_mov_b64_e32 v[76:77], v[12:13]
	v_mov_b64_e32 v[80:81], v[12:13]
	v_mov_b64_e32 v[84:85], v[12:13]
	v_mov_b64_e32 v[88:89], v[12:13]
	v_ashrrev_i32_e32 v227, 6, v0
	v_add_u32_e32 v228, 0x3800, v214
	v_add_u32_e32 v229, 0x3800, v215
	v_add_u32_e32 v230, 0x3800, v219
	v_add_u32_e32 v231, 0x3800, v220
	v_subrev_u32_e32 v232, s2, v223
	s_add_i32 s24, s23, 1
	s_mov_b32 s25, 0
	v_mov_b32_e32 v234, 0xf149f2ca
	v_mov_b32_e32 v233, 0
	s_mov_b32 s26, 63
	v_mov_b32_e32 v0, v225
	v_mov_b32_e32 v164, v224
	v_mov_b64_e32 v[22:23], v[10:11]
	v_mov_b64_e32 v[34:35], v[10:11]
	v_mov_b64_e32 v[38:39], v[10:11]
	v_mov_b64_e32 v[42:43], v[10:11]
	v_mov_b64_e32 v[46:47], v[10:11]
	v_mov_b64_e32 v[50:51], v[10:11]
	v_mov_b64_e32 v[54:55], v[10:11]
	v_mov_b64_e32 v[58:59], v[10:11]
	v_mov_b64_e32 v[62:63], v[10:11]
	v_mov_b64_e32 v[66:67], v[10:11]
	v_mov_b64_e32 v[70:71], v[10:11]
	v_mov_b64_e32 v[74:75], v[10:11]
	v_mov_b64_e32 v[78:79], v[10:11]
	v_mov_b64_e32 v[82:83], v[10:11]
	v_mov_b64_e32 v[86:87], v[10:11]
	v_mov_b32_e32 v235, 0
	v_mov_b32_e32 v236, 0xf149f2ca
	v_lshl_add_u64 v[6:7], v[148:149], 1, s[18:19]
	v_lshl_add_u64 v[2:3], v[146:147], 1, s[18:19]
	global_load_dwordx4 v[2:5], v[2:3], off offset:1024
	s_nop 0
	global_load_dwordx4 v[6:9], v[6:7], off offset:1024
	s_nop 0
	global_load_dwordx4 v[14:17], v[154:155], off
	global_load_dwordx4 v[18:21], v[156:157], off
	global_load_dwordx4 v[26:29], v[158:159], off
	global_load_dwordx4 v[30:33], v[160:161], off
	s_waitcnt vmcnt(9)
	ds_write_b128 v129, v[94:97] offset:44096
	s_waitcnt vmcnt(8)
	ds_write_b128 v129, v[90:93] offset:43072
	s_waitcnt vmcnt(7)
	ds_write_b128 v129, v[98:101] offset:45120
	s_waitcnt vmcnt(6)
	ds_write_b128 v129, v[102:105] offset:46144
	s_waitcnt lgkmcnt(0)
	s_barrier
	s_waitcnt vmcnt(5)
	ds_write_b128 v205, v[2:5]
	s_waitcnt vmcnt(4)
	ds_write_b128 v206, v[6:9]
	s_waitcnt vmcnt(3)
	ds_write2_b64 v228, v[14:15], v[16:17] offset1:2
	s_waitcnt vmcnt(2)
	ds_write2_b64 v229, v[18:19], v[20:21] offset1:2
	s_waitcnt vmcnt(1)
	ds_write2_b64 v230, v[26:27], v[28:29] offset1:2
	s_waitcnt vmcnt(0)
	ds_write2_b64 v231, v[30:31], v[32:33] offset1:2
	s_waitcnt lgkmcnt(0)
	s_barrier
	s_branch .LBB0_533

; __device__ __forceinline__ f32x4 mfma16(bf16x8 a, bf16x8 b, f32x4 c) { return __builtin_amdgcn_mfma_f32_16x16x32_bf16(a, b, c, 0, 0, 0); }
; #define ATT_SCHED_BARRIER __builtin_amdgcn_sched_barrier(0)
; template <int DQK, int DV, int MODE> ...
;     ...
;         for (int t = 0; t < 4; ++t) {
;           {
;             const bf16x8 kf = *(const bf16x8*)(Ks + (t * 16 + fr) * KST + fq * 8);
; #pragma unroll
;             for (int qq = 0; qq < QG; ++qq) S[qq][t] = __builtin_amdgcn_mfma_f32_16x16x32_bf16(kf, *(const bf16x8*)(Qs2 + ((q0 + qq) * NKS) * 512), (f32x4){0.f, 0.f, 0.f, 0.f}, 0, 0, 0);
;           }
; #pragma unroll
;           for (int ks = 1; ks < NKS; ++ks) {
;             const bf16x8 kf = *(const bf16x8*)(Ks + (t * 16 + fr) * KST + ks * 32 + fq * 8);
; #pragma unroll
;             for (int qq = 0; qq < QG; ++qq) S[qq][t] = mfma16(kf, *(const bf16x8*)(Qs2 + ((q0 + qq) * NKS + ks) * 512), S[qq][t]);
;           }
;         }
;         ATT_SCHED_BARRIER;
;         bf16x8 pf[QG][2];
; #pragma unroll
;         for (int qq = 0; qq < QG; ++qq) {
;           const int qi = q0 + qq;
;           const int qrow = w * 32 + qi * 16 + fr;
;           f32x4 P[4];
;           float mn;
;           if (path == 0) {
;             float mx = fmax3(S[qq][0][0], S[qq][0][1], S[qq][0][2]);
;             mx = fmax3(mx, S[qq][0][3], S[qq][1][0]); mx = fmax3(mx, S[qq][1][1], S[qq][1][2]); mx = fmax3(mx, S[qq][1][3], S[qq][2][0]);
;             mx = fmax3(mx, S[qq][2][1], S[qq][2][2]); mx = fmax3(mx, S[qq][2][3], S[qq][3][0]); mx = fmax3(mx, S[qq][3][1], S[qq][3][2]);
;             mx = fmax3(mx, S[qq][3][3], mx);
;             mx = xmax_rows(mx);
;             mn = fmax3(mrow[qi], mx * c1 + cb, mrow[qi]);
;             const float off = cb - mn;
; #pragma unroll
;             for (int t = 0; t < 4; ++t) P[t] = S[qq][t] * c1 + off;
;           } else {
;             float mx = -1e30f;
; #pragma unroll
;             for (int t = 0; t < 4; ++t)
; #pragma unroll
;               for (int r = 0; r < 4; ++r) {
;                 const int j = kt * 64 + t * 16 + fq * 4 + r;
;                 float sx = S[qq][t][r] * c1;
;                 if (MODE == 1) {
;                   const int dist = qpos0 + qrow - j;
;                   sx += bias_lds[min(max(dist, 0), 2047)];
;                   if (need_mask && dist < 0) sx = -1e30f;
.LBB0_538:
	s_or_b64 exec, exec, s[4:5]
	ds_read_b128 v[114:117], v90
	ds_read_b128 v[170:173], v90 offset:1024
	ds_read_b128 v[166:169], v90 offset:2048
	ds_read_b128 v[174:177], v90 offset:3072
	ds_read_b128 v[92:95], v207
	ds_read_b128 v[102:105], v207 offset:64
	s_xor_b64 s[4:5], s[12:13], -1
	v_cmp_gt_i32_e32 vcc, s26, v226
	s_waitcnt lgkmcnt(0)
	v_mfma_f32_16x16x32_bf16 v[96:99], v[92:95], v[114:117], 0
	ds_read_b128 v[178:181], v207 offset:5184
	v_mfma_f32_16x16x32_bf16 v[92:95], v[92:95], v[166:169], 0
	v_mfma_f32_16x16x32_bf16 v[110:113], v[102:105], v[174:177], v[92:95]
	v_mfma_f32_16x16x32_bf16 v[98:101], v[102:105], v[170:173], v[96:99]
	s_nop 5
	ds_read_b128 v[90:93], v207 offset:2560
	ds_read_b128 v[102:105], v207 offset:2624
	s_waitcnt lgkmcnt(1)
	v_mfma_f32_16x16x32_bf16 v[94:97], v[90:93], v[114:117], 0
	v_mfma_f32_16x16x32_bf16 v[90:93], v[90:93], v[166:169], 0
	s_waitcnt lgkmcnt(0)
	v_mfma_f32_16x16x32_bf16 v[106:109], v[102:105], v[174:177], v[90:93]
	v_mfma_f32_16x16x32_bf16 v[118:121], v[102:105], v[170:173], v[94:97]
	s_nop 4
	ds_read_b128 v[90:93], v207 offset:5120
	s_waitcnt lgkmcnt(0)
	v_mfma_f32_16x16x32_bf16 v[94:97], v[90:93], v[114:117], 0
	v_mfma_f32_16x16x32_bf16 v[102:105], v[90:93], v[166:169], 0
	v_mfma_f32_16x16x32_bf16 v[90:93], v[178:181], v[170:173], v[94:97]
	s_nop 5
	ds_read_b128 v[94:97], v207 offset:7680
	s_waitcnt lgkmcnt(0)
	v_mfma_f32_16x16x32_bf16 v[114:117], v[94:97], v[114:117], 0
	v_mfma_f32_16x16x32_bf16 v[94:97], v[94:97], v[166:169], 0
	ds_read_b128 v[166:169], v207 offset:7744
	v_mfma_f32_16x16x32_bf16 v[102:105], v[178:181], v[174:177], v[102:105]
	s_waitcnt lgkmcnt(0)
	v_mfma_f32_16x16x32_bf16 v[114:117], v[166:169], v[170:173], v[114:117]
	v_mfma_f32_16x16x32_bf16 v[94:97], v[166:169], v[174:177], v[94:97]
	v_add_u32_e32 v246, v222, v232
	s_and_saveexec_b64 s[12:13], s[4:5]
	s_xor_b64 s[20:21], exec, s[12:13]
	s_cbranch_execz .LBB0_540
	s_cbranch_vccz .Lb1a_q1
	v_add_u32_e32 v245, 63, v246
	v_add_u32_e32 v244, 62, v246
	v_add_u32_e32 v243, 61, v246
	v_add_u32_e32 v241, 60, v246
	v_add_u32_e32 v240, 47, v246
	v_add_u32_e32 v239, 46, v246
	v_add_u32_e32 v238, 45, v246
	v_add_u32_e32 v237, 44, v246
	v_add_u32_e32 v188, 31, v246
	v_add_u32_e32 v186, 30, v246
	v_add_u32_e32 v184, 29, v246
	v_add_u32_e32 v182, 28, v246
	v_med3_i32 v165, v245, 0, v198
	v_med3_i32 v166, v244, 0, v198
	v_med3_i32 v167, v243, 0, v198
	v_med3_i32 v168, v241, 0, v198
	v_med3_i32 v169, v240, 0, v198
	v_med3_i32 v170, v239, 0, v198
	v_med3_i32 v171, v238, 0, v198
	v_med3_i32 v172, v237, 0, v198
	v_lshl_add_u32 v165, v165, 2, 0
	v_lshl_add_u32 v166, v166, 2, 0
	v_lshl_add_u32 v167, v167, 2, 0
	v_lshl_add_u32 v168, v168, 2, 0
	v_lshl_add_u32 v169, v169, 2, 0
	v_lshl_add_u32 v170, v170, 2, 0
	v_lshl_add_u32 v171, v171, 2, 0
	v_lshl_add_u32 v172, v172, 2, 0
	ds_read_b32 v165, v165 offset:34816
	ds_read_b32 v166, v166 offset:34816
	ds_read_b32 v167, v167 offset:34816
	ds_read_b32 v168, v168 offset:34816
	ds_read_b32 v169, v169 offset:34816
	ds_read_b32 v170, v170 offset:34816
	ds_read_b32 v171, v171 offset:34816
	ds_read_b32 v172, v172 offset:34816
	v_cmp_gt_i32_e64 s[12:13], 0, v245
	s_waitcnt lgkmcnt(7)
	v_fmac_f32_e32 v165, 0x3e38aa3b, v98
	s_and_b64 s[12:13], vcc, s[12:13]
	v_cndmask_b32_e64 v98, v165, v194, s[12:13]
	v_cmp_gt_i32_e64 s[12:13], 0, v244
	s_waitcnt lgkmcnt(6)
	v_fmac_f32_e32 v166, 0x3e38aa3b, v99
	s_and_b64 s[12:13], vcc, s[12:13]
	v_cndmask_b32_e64 v99, v166, v194, s[12:13]
	v_cmp_gt_i32_e64 s[12:13], 0, v243
	s_waitcnt lgkmcnt(5)
	v_fmac_f32_e32 v167, 0x3e38aa3b, v100
	s_and_b64 s[12:13], vcc, s[12:13]
	v_cndmask_b32_e64 v100, v167, v194, s[12:13]
	v_cmp_gt_i32_e64 s[12:13], 0, v241
	s_waitcnt lgkmcnt(4)
	v_fmac_f32_e32 v168, 0x3e38aa3b, v101
	s_and_b64 s[12:13], vcc, s[12:13]
	v_cndmask_b32_e64 v101, v168, v194, s[12:13]
	v_cmp_gt_i32_e64 s[12:13], 0, v240
	s_waitcnt lgkmcnt(3)
	v_fmac_f32_e32 v169, 0x3e38aa3b, v118
	s_and_b64 s[12:13], vcc, s[12:13]
	v_cndmask_b32_e64 v118, v169, v194, s[12:13]
	v_cmp_gt_i32_e64 s[12:13], 0, v239
	s_waitcnt lgkmcnt(2)
	v_fmac_f32_e32 v170, 0x3e38aa3b, v119
	s_and_b64 s[12:13], vcc, s[12:13]
	v_cndmask_b32_e64 v119, v170, v194, s[12:13]
	v_cmp_gt_i32_e64 s[12:13], 0, v238
	s_waitcnt lgkmcnt(1)
	v_fmac_f32_e32 v171, 0x3e38aa3b, v120
	s_and_b64 s[12:13], vcc, s[12:13]
	v_cndmask_b32_e64 v120, v171, v194, s[12:13]
	v_cmp_gt_i32_e64 s[12:13], 0, v237
	s_waitcnt lgkmcnt(0)
; __device__ __forceinline__ float fmax3(float a, float b, float c) { float r; asm("v_max3_f32 %0, %1, %2, %3" : "=v"(r) : "v"(a), "v"(b), "v"(c)); return r; }
; template <int DQK, int DV, int MODE> ...
;     ...
;           if (path == 0) {
;             float mx = fmax3(S[qq][0][0], S[qq][0][1], S[qq][0][2]);
;             mx = fmax3(mx, S[qq][0][3], S[qq][1][0]); mx = fmax3(mx, S[qq][1][1], S[qq][1][2]); mx = fmax3(mx, S[qq][1][3], S[qq][2][0]);
;             mx = fmax3(mx, S[qq][2][1], S[qq][2][2]); mx = fmax3(mx, S[qq][2][3], S[qq][3][0]); mx = fmax3(mx, S[qq][3][1], S[qq][3][2]);
;             mx = fmax3(mx, S[qq][3][3], mx);
;             mx = xmax_rows(mx);
;             mn = fmax3(mrow[qi], mx * c1 + cb, mrow[qi]);
;             const float off = cb - mn;
; #pragma unroll
;             for (int t = 0; t < 4; ++t) P[t] = S[qq][t] * c1 + off;
;           } else {
;             float mx = -1e30f;
; #pragma unroll
;             for (int t = 0; t < 4; ++t)
; #pragma unroll
;               for (int r = 0; r < 4; ++r) {
;                 const int j = kt * 64 + t * 16 + fq * 4 + r;
;                 float sx = S[qq][t][r] * c1;
;                 if (MODE == 1) {
;                   const int dist = qpos0 + qrow - j;
;                   sx += bias_lds[min(max(dist, 0), 2047)];
;                   if (need_mask && dist < 0) sx = -1e30f;
;                 } else if (MODE == 2) {
;                   if ((qpos0 + qrow - j) < 0) sx = -1e30f;
;                 } else {
;                   const int rel = 128 + qrow - j;
;                   sx += bias_lds[min(max(rel, 0), 128)];
;                   if (rel < 0 || rel > 128 || j < jmin) sx = -1e30f;
;                 }
;                 P[t][r] = sx;
;               }
; #pragma unroll
;             for (int t = 0; t < 4; ++t) { mx = fmax3(mx, P[t][0], P[t][1]); mx = fmax3(mx, P[t][2], P[t][3]); }
;             mx = xmax_rows(mx);
;             mn = fmax3(mrow[qi], mx, mx);
; #pragma unroll
;             for (int t = 0; t < 4; ++t) P[t] = P[t] - mn;
	v_fmac_f32_e32 v172, 0x3e38aa3b, v121
	s_and_b64 s[12:13], vcc, s[12:13]
	v_add_u32_e32 v169, 15, v246
	v_add_u32_e32 v171, 14, v246
	v_add_u32_e32 v173, 13, v246
	v_add_u32_e32 v175, 12, v246
	v_cndmask_b32_e64 v121, v172, v194, s[12:13]
	v_med3_i32 v165, v188, 0, v198
	v_med3_i32 v166, v186, 0, v198
	v_med3_i32 v167, v184, 0, v198
	v_med3_i32 v168, v182, 0, v198
	v_med3_i32 v170, v169, 0, v198
	v_med3_i32 v172, v171, 0, v198
	v_med3_i32 v174, v173, 0, v198
	v_med3_i32 v176, v175, 0, v198
	v_lshl_add_u32 v165, v165, 2, 0
	v_lshl_add_u32 v166, v166, 2, 0
	v_lshl_add_u32 v167, v167, 2, 0
	v_lshl_add_u32 v168, v168, 2, 0
	v_lshl_add_u32 v170, v170, 2, 0
	v_lshl_add_u32 v172, v172, 2, 0
	v_lshl_add_u32 v174, v174, 2, 0
	v_lshl_add_u32 v176, v176, 2, 0
	ds_read_b32 v165, v165 offset:34816
	ds_read_b32 v166, v166 offset:34816
	ds_read_b32 v167, v167 offset:34816
	ds_read_b32 v168, v168 offset:34816
	ds_read_b32 v170, v170 offset:34816
	ds_read_b32 v172, v172 offset:34816
	ds_read_b32 v174, v174 offset:34816
	ds_read_b32 v176, v176 offset:34816
	v_cmp_gt_i32_e64 s[12:13], 0, v188
	s_waitcnt lgkmcnt(7)
	v_fmac_f32_e32 v165, 0x3e38aa3b, v90
	s_and_b64 s[12:13], vcc, s[12:13]
	v_cndmask_b32_e64 v90, v165, v194, s[12:13]
	v_cmp_gt_i32_e64 s[12:13], 0, v186
	s_waitcnt lgkmcnt(6)
	v_fmac_f32_e32 v166, 0x3e38aa3b, v91
	s_and_b64 s[12:13], vcc, s[12:13]
	v_cndmask_b32_e64 v91, v166, v194, s[12:13]
	v_cmp_gt_i32_e64 s[12:13], 0, v184
	s_waitcnt lgkmcnt(5)
	v_fmac_f32_e32 v167, 0x3e38aa3b, v92
	s_and_b64 s[12:13], vcc, s[12:13]
	v_cndmask_b32_e64 v92, v167, v194, s[12:13]
	v_cmp_gt_i32_e64 s[12:13], 0, v182
	s_waitcnt lgkmcnt(4)
	v_fmac_f32_e32 v168, 0x3e38aa3b, v93
	s_and_b64 s[12:13], vcc, s[12:13]
	v_cndmask_b32_e64 v93, v168, v194, s[12:13]
	v_cmp_gt_i32_e64 s[12:13], 0, v169
	s_waitcnt lgkmcnt(3)
	v_fmac_f32_e32 v170, 0x3e38aa3b, v114
	s_and_b64 s[12:13], vcc, s[12:13]
	v_max3_f32 v165, v194, v98, v99
	v_cndmask_b32_e64 v114, v170, v194, s[12:13]
	v_cmp_gt_i32_e64 s[12:13], 0, v171
	v_max3_f32 v165, v165, v100, v101
	s_waitcnt lgkmcnt(2)
	v_fmac_f32_e32 v172, 0x3e38aa3b, v115
	s_and_b64 s[12:13], vcc, s[12:13]
	v_max3_f32 v165, v165, v118, v119
	v_cndmask_b32_e64 v115, v172, v194, s[12:13]
	v_cmp_gt_i32_e64 s[12:13], 0, v173
	v_max3_f32 v165, v165, v120, v121
	s_waitcnt lgkmcnt(1)
	v_fmac_f32_e32 v174, 0x3e38aa3b, v116
	s_and_b64 s[12:13], vcc, s[12:13]
	v_max3_f32 v165, v165, v90, v91
	v_cndmask_b32_e64 v116, v174, v194, s[12:13]
	v_cmp_gt_i32_e64 s[12:13], 0, v175
	v_max3_f32 v165, v165, v92, v93
	s_waitcnt lgkmcnt(0)
	v_fmac_f32_e32 v176, 0x3e38aa3b, v117
	s_and_b64 s[12:13], vcc, s[12:13]
	v_max3_f32 v165, v165, v114, v115
	v_cndmask_b32_e64 v117, v176, v194, s[12:13]
	v_max3_f32 v165, v165, v116, v117
	s_nop 0
	v_mov_b32_e32 v166, v165
	s_nop 1
	v_permlane16_swap_b32_e32 v165, v166
	v_max3_f32 v165, v165, v166, v166
	s_nop 0
	v_mov_b32_e32 v166, v165
	s_nop 1
	v_permlane32_swap_b32_e32 v165, v166
	v_max3_f32 v165, v165, v166, v166
	s_nop 0
	v_max3_f32 v165, v236, v165, v165
	s_nop 0
	v_sub_f32_e32 v176, v98, v165
	v_sub_f32_e32 v177, v99, v165
	v_sub_f32_e32 v172, v100, v165
	v_sub_f32_e32 v173, v101, v165
	v_sub_f32_e32 v166, v118, v165
	v_sub_f32_e32 v167, v119, v165
	v_sub_f32_e32 v174, v120, v165
	v_sub_f32_e32 v175, v121, v165
	v_sub_f32_e32 v170, v90, v165
	v_sub_f32_e32 v171, v91, v165
	v_sub_f32_e32 v180, v92, v165
	v_sub_f32_e32 v181, v93, v165
	v_sub_f32_e32 v178, v114, v165
	v_sub_f32_e32 v179, v115, v165
	v_sub_f32_e32 v168, v116, v165
	v_sub_f32_e32 v169, v117, v165
.LBB0_540:
	s_andn2_saveexec_b64 s[12:13], s[20:21]
	s_cbranch_execz .LBB0_542
	v_max3_f32 v165, v98, v99, v100
	s_mov_b32 s20, 0x3e38aa3b
	v_max3_f32 v165, v165, v101, v118
	v_max3_f32 v165, v165, v119, v120
	v_max3_f32 v165, v165, v121, v90
	v_max3_f32 v165, v165, v91, v92
	v_max3_f32 v165, v165, v93, v114
	v_max3_f32 v165, v165, v115, v116
	v_max3_f32 v165, v165, v117, v165
	v_mov_b32_e32 v166, v165
	s_nop 1
	v_permlane16_swap_b32_e32 v165, v166
	v_max3_f32 v165, v165, v166, v166
	v_mov_b32_e32 v166, v165
	s_nop 1
	v_permlane32_swap_b32_e32 v165, v166
	v_max3_f32 v165, v165, v166, v166
	v_fmamk_f32 v165, v165, 0x3e38aa3b, v242
	v_max3_f32 v165, v236, v165, v236
	v_sub_f32_e32 v176, v242, v165
	v_pk_fma_f32 v[168:169], v[116:117], s[20:21], v[176:177] op_sel_hi:[1,0,0]
	v_pk_fma_f32 v[178:179], v[114:115], s[20:21], v[176:177] op_sel_hi:[1,0,0]
	v_pk_fma_f32 v[180:181], v[92:93], s[20:21], v[176:177] op_sel_hi:[1,0,0]
	v_pk_fma_f32 v[170:171], v[90:91], s[20:21], v[176:177] op_sel_hi:[1,0,0]
	v_pk_fma_f32 v[174:175], v[120:121], s[20:21], v[176:177] op_sel_hi:[1,0,0]
	v_pk_fma_f32 v[166:167], v[118:119], s[20:21], v[176:177] op_sel_hi:[1,0,0]
	v_pk_fma_f32 v[172:173], v[100:101], s[20:21], v[176:177] op_sel_hi:[1,0,0]
	v_pk_fma_f32 v[176:177], v[98:99], s[20:21], v[176:177] op_sel_hi:[1,0,0]

; template <int DQK, int DV, int MODE> ...
;     ...
;           if (path == 0) {
;             float mx = fmax3(S[qq][0][0], S[qq][0][1], S[qq][0][2]);
;             mx = fmax3(mx, S[qq][0][3], S[qq][1][0]); mx = fmax3(mx, S[qq][1][1], S[qq][1][2]); mx = fmax3(mx, S[qq][1][3], S[qq][2][0]);
;             mx = fmax3(mx, S[qq][2][1], S[qq][2][2]); mx = fmax3(mx, S[qq][2][3], S[qq][3][0]); mx = fmax3(mx, S[qq][3][1], S[qq][3][2]);
;             mx = fmax3(mx, S[qq][3][3], mx);
;             mx = xmax_rows(mx);
;             mn = fmax3(mrow[qi], mx * c1 + cb, mrow[qi]);
;             const float off = cb - mn;
; #pragma unroll
;             for (int t = 0; t < 4; ++t) P[t] = S[qq][t] * c1 + off;
;           } else {
;             float mx = -1e30f;
; #pragma unroll
;             for (int t = 0; t < 4; ++t)
; #pragma unroll
;               for (int r = 0; r < 4; ++r) {
;                 const int j = kt * 64 + t * 16 + fq * 4 + r;
;                 float sx = S[qq][t][r] * c1;
;                 if (MODE == 1) {
;                   const int dist = qpos0 + qrow - j;
;                   sx += bias_lds[min(max(dist, 0), 2047)];
;                   if (need_mask && dist < 0) sx = -1e30f;
;                 } else if (MODE == 2) {
;                   if ((qpos0 + qrow - j) < 0) sx = -1e30f;
;                 } else {
;                   const int rel = 128 + qrow - j;
;                   sx += bias_lds[min(max(rel, 0), 128)];
;                   if (rel < 0 || rel > 128 || j < jmin) sx = -1e30f;
;                 }
;                 P[t][r] = sx;
;               }
; #pragma unroll
;             for (int t = 0; t < 4; ++t) { mx = fmax3(mx, P[t][0], P[t][1]); mx = fmax3(mx, P[t][2], P[t][3]); }
;             mx = xmax_rows(mx);
;             mn = fmax3(mrow[qi], mx, mx);
; #pragma unroll
;             for (int t = 0; t < 4; ++t) P[t] = P[t] - mn;
;           }
;           {
;             const float alpha = fexp2(mrow[qi] - mn);
;             lrow[qi] *= alpha;
; #pragma unroll
;             for (int dt = 0; dt < NDT; ++dt) O[qi][dt] *= alpha;
;           }
;           mrow[qi] = mn;
;           f32x4 ls4 = (f32x4){0.f, 0.f, 0.f, 0.f};
; #pragma unroll
;           for (int t = 0; t < 4; ++t) {
; #pragma unroll
;             for (int r = 0; r < 4; ++r) P[t][r] = fexp2(P[t][r]);
;             ls4 += P[t];
;           }
;           lrow[qi] += (ls4[0] + ls4[1]) + (ls4[2] + ls4[3]);
.LBB0_544:
	s_andn2_saveexec_b64 s[4:5], s[4:5]
	s_cbranch_execz .LBB0_546
	v_max3_f32 v114, v110, v111, v112
	s_mov_b32 s12, 0x3e38aa3b
	v_max3_f32 v114, v114, v113, v106
	v_max3_f32 v114, v114, v107, v108
	v_max3_f32 v114, v114, v109, v102
	v_max3_f32 v114, v114, v103, v104
	v_max3_f32 v114, v114, v105, v94
	v_max3_f32 v114, v114, v95, v96
	v_max3_f32 v114, v114, v97, v114
	v_mov_b32_e32 v115, v114
	s_nop 1
	v_permlane16_swap_b32_e32 v114, v115
	v_max3_f32 v114, v114, v115, v115
	v_mov_b32_e32 v115, v114
	s_nop 1
	v_permlane32_swap_b32_e32 v114, v115
	v_max3_f32 v114, v114, v115, v115
	v_fmamk_f32 v114, v114, 0x3e38aa3b, v242
	v_max3_f32 v247, v234, v114, v234
	v_sub_f32_e32 v114, v242, v247
	v_pk_fma_f32 v[186:187], v[112:113], s[12:13], v[114:115] op_sel_hi:[1,0,0]
	v_pk_fma_f32 v[188:189], v[110:111], s[12:13], v[114:115] op_sel_hi:[1,0,0]
	v_pk_fma_f32 v[182:183], v[108:109], s[12:13], v[114:115] op_sel_hi:[1,0,0]
	v_pk_fma_f32 v[184:185], v[106:107], s[12:13], v[114:115] op_sel_hi:[1,0,0]
	v_pk_fma_f32 v[178:179], v[104:105], s[12:13], v[114:115] op_sel_hi:[1,0,0]
	v_pk_fma_f32 v[180:181], v[102:103], s[12:13], v[114:115] op_sel_hi:[1,0,0]
	v_pk_fma_f32 v[116:117], v[96:97], s[12:13], v[114:115] op_sel_hi:[1,0,0]
	v_pk_fma_f32 v[114:115], v[94:95], s[12:13], v[114:115] op_sel_hi:[1,0,0]
.LBB0_546:
	s_or_b64 exec, exec, s[4:5]
	v_sub_f32_e32 v94, v236, v165
	v_cmp_neq_f32_e32 vcc, v236, v165
	v_exp_f32_e32 v94, v94
	v_pk_add_f32 v[96:97], v[166:167], v[176:177]
	v_pk_add_f32 v[102:103], v[174:175], v[172:173]
	v_pk_add_f32 v[96:97], v[170:171], v[96:97]
	v_pk_add_f32 v[102:103], v[120:121], v[102:103]
	v_pk_add_f32 v[96:97], v[118:119], v[96:97]
	v_pk_add_f32 v[102:103], v[168:169], v[102:103]
	s_cbranch_vccz .Lb_skip_r1
	v_mul_f32_e32 v88, v88, v94
	v_mul_f32_e32 v89, v89, v94
	v_mul_f32_e32 v86, v86, v94
	v_mul_f32_e32 v87, v87, v94
	v_mul_f32_e32 v84, v84, v94
	v_mul_f32_e32 v85, v85, v94
	v_mul_f32_e32 v82, v82, v94
	v_mul_f32_e32 v83, v83, v94
	v_mul_f32_e32 v80, v80, v94
	v_mul_f32_e32 v81, v81, v94
	v_mul_f32_e32 v78, v78, v94
	v_mul_f32_e32 v79, v79, v94
	v_mul_f32_e32 v76, v76, v94
	v_mul_f32_e32 v77, v77, v94
	v_mul_f32_e32 v74, v74, v94
	v_mul_f32_e32 v75, v75, v94
	v_mul_f32_e32 v72, v72, v94
	v_mul_f32_e32 v73, v73, v94
	v_mul_f32_e32 v70, v70, v94
	v_mul_f32_e32 v71, v71, v94
	v_mul_f32_e32 v68, v68, v94
	v_mul_f32_e32 v69, v69, v94
	v_mul_f32_e32 v66, v66, v94
	v_mul_f32_e32 v67, v67, v94
	v_mul_f32_e32 v64, v64, v94
	v_mul_f32_e32 v65, v65, v94
	v_mul_f32_e32 v62, v62, v94
	v_mul_f32_e32 v63, v63, v94
	v_mul_f32_e32 v60, v60, v94
	v_mul_f32_e32 v61, v61, v94
	v_mul_f32_e32 v58, v58, v94
	v_mul_f32_e32 v59, v59, v94
.Lb_skip_r1:
	v_add_f32_e32 v95, v96, v97
	v_add_f32_e32 v97, v102, v103
	v_add_f32_e32 v166, v95, v97
	v_fmac_f32_e32 v166, v235, v94
	v_exp_f32_e32 v94, v188
	v_exp_f32_e32 v95, v189
	v_exp_f32_e32 v102, v186
	v_exp_f32_e32 v103, v187
	v_exp_f32_e32 v104, v184
	v_exp_f32_e32 v106, v182
	v_exp_f32_e32 v107, v183
	v_exp_f32_e32 v105, v185
	v_exp_f32_e32 v112, v180
	v_exp_f32_e32 v113, v181
	v_exp_f32_e32 v118, v178
	v_exp_f32_e32 v119, v179
	v_exp_f32_e32 v114, v114
	v_exp_f32_e32 v116, v116
	v_exp_f32_e32 v117, v117
	v_exp_f32_e32 v115, v115
	v_sub_f32_e32 v96, v234, v247
	v_cmp_neq_f32_e32 vcc, v234, v247
	v_exp_f32_e32 v96, v96
	v_pk_add_f32 v[108:109], v[104:105], v[94:95]
	v_pk_add_f32 v[110:111], v[106:107], v[102:103]
	v_pk_add_f32 v[108:109], v[112:113], v[108:109]
	v_pk_add_f32 v[110:111], v[118:119], v[110:111]
	v_pk_add_f32 v[108:109], v[114:115], v[108:109]
	v_pk_add_f32 v[110:111], v[116:117], v[110:111]
	s_cbranch_vccz .Lb_skip_r2
	v_mul_f32_e32 v56, v56, v96
	v_mul_f32_e32 v57, v57, v96
	v_mul_f32_e32 v54, v54, v96
	v_mul_f32_e32 v55, v55, v96
	v_mul_f32_e32 v52, v52, v96
	v_mul_f32_e32 v53, v53, v96
	v_mul_f32_e32 v50, v50, v96
	v_mul_f32_e32 v51, v51, v96
	v_mul_f32_e32 v48, v48, v96
	v_mul_f32_e32 v49, v49, v96
	v_mul_f32_e32 v46, v46, v96
	v_mul_f32_e32 v47, v47, v96
	v_mul_f32_e32 v44, v44, v96
	v_mul_f32_e32 v45, v45, v96
	v_mul_f32_e32 v42, v42, v96
	v_mul_f32_e32 v43, v43, v96
	v_mul_f32_e32 v40, v40, v96
	v_mul_f32_e32 v41, v41, v96
	v_mul_f32_e32 v38, v38, v96
	v_mul_f32_e32 v39, v39, v96
	v_mul_f32_e32 v36, v36, v96
	v_mul_f32_e32 v37, v37, v96
	v_mul_f32_e32 v34, v34, v96
	v_mul_f32_e32 v35, v35, v96
	v_mul_f32_e32 v24, v24, v96
	v_mul_f32_e32 v25, v25, v96
	v_mul_f32_e32 v22, v22, v96
	v_mul_f32_e32 v23, v23, v96
	v_mul_f32_e32 v12, v12, v96
	v_mul_f32_e32 v13, v13, v96
	v_mul_f32_e32 v10, v10, v96
	v_mul_f32_e32 v11, v11, v96
; __device__ __forceinline__ unsigned pack2(float lo, float hi) { unsigned r; asm("v_cvt_pk_bf16_f32 %0, %1, %2" : "=v"(r) : "v"(lo), "v"(hi)); return r; }
; __device__ __forceinline__ f32x4 mfma16(bf16x8 a, bf16x8 b, f32x4 c) { return __builtin_amdgcn_mfma_f32_16x16x32_bf16(a, b, c, 0, 0, 0); }
; #define ATT_SCHED_BARRIER __builtin_amdgcn_sched_barrier(0)
; template <int DQK, int DV, int MODE> ...
;     ...
;           lrow[qi] += (ls4[0] + ls4[1]) + (ls4[2] + ls4[3]);
; #pragma unroll
;           for (int s2 = 0; s2 < 2; ++s2) {
;             u32x4 pk;
;             pk.x = pack2(P[2 * s2][0], P[2 * s2][1]); pk.y = pack2(P[2 * s2][2], P[2 * s2][3]);
;             pk.z = pack2(P[2 * s2 + 1][0], P[2 * s2 + 1][1]); pk.w = pack2(P[2 * s2 + 1][2], P[2 * s2 + 1][3]);
;             pf[qq][s2] = __builtin_bit_cast(bf16x8, pk);
;           }
;           ATT_SCHED_BARRIER;
;         }
; #pragma unroll
;         for (int s2 = 0; s2 < 2; ++s2)
; #pragma unroll
;           for (int dt = 0; dt < NDT; ++dt) {
;             const bf16x8 vf = *(const bf16x8*)(Vt + (dt * 16 + fr) * VTS + s2 * 32 + fq * 8);
; #pragma unroll
;             for (int qq = 0; qq < QG; ++qq) O[q0 + qq][dt] = mfma16(vf, pf[qq][s2], O[q0 + qq][dt]);
;             if ((dt & (ATT_PVB - 1)) == (ATT_PVB - 1)) ATT_SCHED_BARRIER;
;           }
.Lb_skip_r2:
	v_add_f32_e32 v108, v108, v109
	v_add_f32_e32 v109, v110, v111
	v_add_f32_e32 v110, v108, v109
	v_fmac_f32_e32 v110, v233, v96
	v_cvt_pk_bf16_f32 v94, v94, v95
	v_cvt_pk_bf16_f32 v95, v102, v103
	v_cvt_pk_bf16_f32 v96, v104, v105
	v_cvt_pk_bf16_f32 v97, v106, v107
	v_cvt_pk_bf16_f32 v102, v112, v113
	v_cvt_pk_bf16_f32 v103, v118, v119
	v_cvt_pk_bf16_f32 v104, v114, v115
	v_cvt_pk_bf16_f32 v105, v116, v117
	ds_read_b128 v[106:109], v208 offset:14336
	ds_read_b128 v[114:117], v208 offset:16896
	ds_read_b128 v[118:121], v208 offset:19456
	ds_read_b128 v[170:173], v208 offset:22016
	ds_read_b128 v[174:177], v208 offset:24576
	ds_read_b128 v[178:181], v208 offset:27136
	ds_read_b128 v[182:185], v208 offset:29696
	ds_read_b128 v[186:189], v208 offset:32256
	s_waitcnt lgkmcnt(7)
	v_mfma_f32_16x16x32_bf16 v[86:89], v[106:109], v[98:101], v[86:89]
	v_mfma_f32_16x16x32_bf16 v[54:57], v[106:109], v[94:97], v[54:57]
	ds_read_b128 v[106:109], v208 offset:14400
	s_waitcnt lgkmcnt(7)
	v_mfma_f32_16x16x32_bf16 v[82:85], v[114:117], v[98:101], v[82:85]
	v_mfma_f32_16x16x32_bf16 v[50:53], v[114:117], v[94:97], v[50:53]
	ds_read_b128 v[114:117], v208 offset:16960
	s_waitcnt lgkmcnt(7)
	v_mfma_f32_16x16x32_bf16 v[78:81], v[118:121], v[98:101], v[78:81]
	v_mfma_f32_16x16x32_bf16 v[46:49], v[118:121], v[94:97], v[46:49]
	ds_read_b128 v[118:121], v208 offset:19520
	s_waitcnt lgkmcnt(7)
	v_mfma_f32_16x16x32_bf16 v[74:77], v[170:173], v[98:101], v[74:77]
	v_mfma_f32_16x16x32_bf16 v[42:45], v[170:173], v[94:97], v[42:45]
	ds_read_b128 v[170:173], v208 offset:22080
	s_waitcnt lgkmcnt(7)
	v_mfma_f32_16x16x32_bf16 v[70:73], v[174:177], v[98:101], v[70:73]
	v_mfma_f32_16x16x32_bf16 v[38:41], v[174:177], v[94:97], v[38:41]
	ds_read_b128 v[174:177], v208 offset:24640
	s_waitcnt lgkmcnt(7)
	v_mfma_f32_16x16x32_bf16 v[66:69], v[178:181], v[98:101], v[66:69]
	v_mfma_f32_16x16x32_bf16 v[34:37], v[178:181], v[94:97], v[34:37]
	ds_read_b128 v[178:181], v208 offset:27200
	s_waitcnt lgkmcnt(7)
	v_mfma_f32_16x16x32_bf16 v[62:65], v[182:185], v[98:101], v[62:65]
	v_mfma_f32_16x16x32_bf16 v[22:25], v[182:185], v[94:97], v[22:25]
	ds_read_b128 v[182:185], v208 offset:29760
	s_waitcnt lgkmcnt(7)
	v_mfma_f32_16x16x32_bf16 v[58:61], v[186:189], v[98:101], v[58:61]
	v_mfma_f32_16x16x32_bf16 v[10:13], v[186:189], v[94:97], v[10:13]
	ds_read_b128 v[186:189], v208 offset:32320
	s_waitcnt lgkmcnt(7)
	v_mfma_f32_16x16x32_bf16 v[86:89], v[106:109], v[90:93], v[86:89]
	v_mfma_f32_16x16x32_bf16 v[54:57], v[106:109], v[102:105], v[54:57]
	s_waitcnt lgkmcnt(6)
	v_mfma_f32_16x16x32_bf16 v[82:85], v[114:117], v[90:93], v[82:85]
	v_mfma_f32_16x16x32_bf16 v[50:53], v[114:117], v[102:105], v[50:53]
	s_waitcnt lgkmcnt(5)
	v_mfma_f32_16x16x32_bf16 v[78:81], v[118:121], v[90:93], v[78:81]
	v_mfma_f32_16x16x32_bf16 v[46:49], v[118:121], v[102:105], v[46:49]
	s_waitcnt lgkmcnt(4)
	v_mfma_f32_16x16x32_bf16 v[74:77], v[170:173], v[90:93], v[74:77]
	v_mfma_f32_16x16x32_bf16 v[42:45], v[170:173], v[102:105], v[42:45]
	s_waitcnt lgkmcnt(3)
	v_mfma_f32_16x16x32_bf16 v[70:73], v[174:177], v[90:93], v[70:73]
	v_mfma_f32_16x16x32_bf16 v[38:41], v[174:177], v[102:105], v[38:41]
	s_waitcnt lgkmcnt(2)
	v_mfma_f32_16x16x32_bf16 v[66:69], v[178:181], v[90:93], v[66:69]
	v_mfma_f32_16x16x32_bf16 v[34:37], v[178:181], v[102:105], v[34:37]
	s_waitcnt lgkmcnt(1)
	v_mfma_f32_16x16x32_bf16 v[62:65], v[182:185], v[90:93], v[62:65]
	v_mfma_f32_16x16x32_bf16 v[22:25], v[182:185], v[102:105], v[22:25]
	s_waitcnt lgkmcnt(0)
	v_mfma_f32_16x16x32_bf16 v[58:61], v[186:189], v[90:93], v[58:61]
	v_mfma_f32_16x16x32_bf16 v[10:13], v[186:189], v[102:105], v[10:13]
	v_mov_b32_e32 v236, v165
	v_mov_b32_e32 v234, v247
	v_mov_b32_e32 v235, v166
	v_mov_b32_e32 v233, v110

; template <int DQK, int DV, int MODE> ...
;     ...
;   bf16_t* Qs = (bf16_t*)(smem + ATT_Q_OFF) + (w * 2 * NKS) * 512 + lane * 8;
; #pragma unroll
;   for (int qi = 0; qi < 2; ++qi)
; #pragma unroll
;     for (int ks = 0; ks < NKS; ++ks)
;       *(bf16x8*)(Qs + (qi * NKS + ks) * 512) = *(const bf16x8*)(Qp + (unsigned)((w * 32 + qi * 16 + fr) * qrs + ks * 32 + fq * 8));
; #pragma unroll
;   for (int qi = 0; qi < 2; ++qi) {
;     mrow[qi] = -1e30f; lrow[qi] = 0.f;
; #pragma unroll
;     for (int dt = 0; dt < NDT; ++dt) O[qi][dt] = (f32x4){0.f, 0.f, 0.f, 0.f};
;   }
;   int wkb, wke;
;   if (MODE == 0) { wkb = max(kt_begin, w >> 1); wke = (w * 32 + 159) / 64 + 1; }
;   else { wkb = 0; wke = (qpos0 + w * 32 + 31) / 64 + 1; }
;   u32x4 rk[NKC], rv[NVC];
;   auto gload = [&](int kt) {
; #pragma unroll
;     for (int i = 0; i < NKC; ++i) { const int c = tid + 256 * i, key = c / KCH, part = c % KCH; rk[i] = *(const u32x4*)(Kp + (unsigned)((kt * 64 + key) * krs + part * 8)); }
;     if (MODE == 0) {
; #pragma unroll
;       for (int i = 0; i < NVC; ++i) { const int c = tid + 256 * i, key = c >> 3, part = c & 7; rv[i] = *(const u32x4*)(Vp + (unsigned)((kt * 64 + key) * vrs + part * 8)); }
;     } else {
; #pragma unroll
;       for (int i = 0; i < NVC; ++i) { const int c = tid + 256 * i, dv = c >> 3, kc = c & 7; rv[i] = *(const u32x4*)(Vp + (unsigned)(dv * vrs + kt * 64 + kc * 8)); }
;     }
;   };
;   auto sstore = [&]() {
; #pragma unroll
;     for (int i = 0; i < NKC; ++i) { const int c = tid + 256 * i, key = c / KCH, part = c % KCH; *(u32x4*)(Ks + key * KST + part * 8) = rk[i]; }
;     if (MODE == 0) {
; #pragma unroll
;       for (int i = 0; i < NVC; ++i) {
;         const int c = tid + 256 * i, key = c >> 3, part = c & 7;
;         const int pos = (key & 32) + ((key >> 2) & 3) * 8 + ((key >> 4) & 1) * 4 + (key & 3);
; #pragma unroll
;         for (int e = 0; e < 8; ++e) Vt[(part * 8 + e) * VTS + pos] = (bf16_t)(rv[i][e >> 1] >> ((e & 1) * 16));
;       }
;     } else {
; #pragma unroll
;       for (int i = 0; i < NVC; ++i) {
;         const int c = tid + 256 * i, dv = c >> 3, kc = c & 7;
;         const int pos0 = (kc >> 2) * 32 + ((kc & 1) * 2) * 8 + ((kc >> 1) & 1) * 4;
;         *(u32x2*)(Vt + dv * VTS + pos0) = (u32x2){rv[i].x, rv[i].y};
;         *(u32x2*)(Vt + dv * VTS + pos0 + 8) = (u32x2){rv[i].z, rv[i].w};
;       }
;     }
;   };
;   gload(kt_begin);
.LBB0_557:
	s_or_b64 exec, exec, s[0:1]
	s_waitcnt lgkmcnt(0)
	s_barrier
	ds_read_b32 v0, v1 offset:43008
	s_movk_i32 s0, 0x60
	s_waitcnt lgkmcnt(0)
	v_cmp_gt_i32_e32 vcc, s0, v0
	v_readfirstlane_b32 s2, v0
	s_mov_b64 s[0:1], -1
	s_cbranch_vccz .LBB0_552
	s_mul_hi_i32 s0, s2, 0x55555556
	s_lshr_b32 s1, s0, 31
	s_add_i32 s0, s0, s1
	s_mul_i32 s1, s0, 3
	s_sub_i32 s1, s2, s1
	s_lshl_b32 s0, s0, 1
	v_readlane_b32 s3, v252, 46
	s_add_i32 s2, s0, s1
	s_or_b32 s0, s0, s3
	s_cmp_lt_i32 s1, 2
	s_cselect_b32 s0, s2, s0
	v_readlane_b32 s1, v253, 13
	v_readlane_b32 s2, v252, 45
	s_cselect_b32 s2, s1, s2
	s_mul_hi_u32 s3, s2, 0x2aaaaaab
	s_mul_i32 s1, s3, 6
	s_lshl_b32 s0, s0, 7
	s_sub_i32 s14, s2, s1
	s_lshl_b32 s1, s3, 13
	s_sub_i32 s6, 0x1f80, s0
	s_add_u32 s10, s1, s6
	s_addc_u32 s11, 0, 0
	s_sub_i32 s0, 0x1fc0, s0
	s_lshr_b32 s16, s0, 6
	s_mul_i32 s0, s11, 0x480
	s_mul_hi_u32 s1, s10, 0x480
	s_add_i32 s1, s1, s0
	s_mul_i32 s0, s10, 0x480
	s_add_u32 s4, s80, s0
	s_mul_i32 s74, s14, 0x60
	s_addc_u32 s5, s81, s1
	s_lshl_b64 s[0:1], s[74:75], 1
	s_add_u32 s4, s4, s0
	s_addc_u32 s5, s5, s1
	s_waitcnt vmcnt(0)
	v_lshl_add_u64 v[2:3], v[88:89], 1, s[4:5]
	v_lshl_add_u64 v[26:27], v[90:91], 1, s[4:5]
	v_lshl_add_u64 v[30:31], v[92:93], 1, s[4:5]
	v_lshl_add_u64 v[38:39], v[94:95], 1, s[4:5]
	global_load_dwordx4 v[22:25], v[2:3], off offset:64
	global_load_dwordx4 v[2:5], v[2:3], off
	global_load_dwordx4 v[26:29], v[26:27], off
	global_load_dwordx4 v[34:37], v[30:31], off offset:64
	global_load_dwordx4 v[30:33], v[30:31], off
	global_load_dwordx4 v[38:41], v[38:39], off
	s_mul_i32 s3, s3, 0x900000
	s_add_u32 s3, s82, s3
	s_addc_u32 s7, s83, 0
	s_add_u32 s0, s3, s0
	s_addc_u32 s1, s7, s1
	s_lshl_b32 s2, s2, 20
	s_add_u32 s2, s84, s2
	s_addc_u32 s3, s85, 0
	v_lshl_add_u64 v[14:15], v[136:137], 1, s[2:3]
	v_lshl_add_u64 v[18:19], v[138:139], 1, s[2:3]
	v_lshl_add_u64 v[10:11], v[100:101], 1, s[0:1]
	global_load_dwordx4 v[14:17], v[14:15], off
	v_add_u32_e32 v170, s6, v212
	global_load_dwordx4 v[18:21], v[18:19], off
	v_ashrrev_i32_e32 v0, 31, v170
	global_load_dwordx4 v[10:13], v[10:11], off
	v_lshl_add_u64 v[6:7], v[98:99], 1, s[0:1]
	v_lshl_add_u64 v[42:43], v[96:97], 1, s[0:1]
	global_load_dwordx4 v[6:9], v[6:7], off
	global_load_dwordx4 v[42:45], v[42:43], off
	v_lshrrev_b32_e32 v0, 26, v0
	v_add3_u32 v0, v0, v170, 31
	v_ashrrev_i32_e32 v171, 6, v0
	v_add_u32_e32 v172, 0x3800, v214
	v_add_u32_e32 v173, 0x3800, v215
	v_or_b32_e32 v0, s6, v209
	v_add_u32_e32 v102, v0, v212
	v_or_b32_e32 v167, 16, v102
	v_mov_b32_e32 v103, v102
	v_add_u32_e32 v105, 13, v102
	v_add_u32_e32 v104, 14, v102
	s_mov_b32 s17, 0
	v_mov_b32_e32 v166, 0xf149f2ca
	v_mov_b32_e32 v165, 0
	s_mov_b32 s15, 63
	v_mov_b32_e32 v0, v164
	v_mov_b32_e32 v106, v163
	v_mov_b32_e32 v108, v162
	v_mov_b32_e32 v168, 0
	v_mov_b32_e32 v169, 0xf149f2ca
	s_waitcnt vmcnt(10)
	ds_write_b128 v152, v[22:25] offset:44096
	s_waitcnt vmcnt(9)
	ds_write_b128 v152, v[2:5] offset:43072
	s_waitcnt vmcnt(8)
	ds_write_b128 v152, v[26:29] offset:45120
	s_waitcnt vmcnt(7)
	ds_write_b128 v152, v[34:37] offset:47168
	s_waitcnt vmcnt(6)
	ds_write_b128 v152, v[30:33] offset:46144
	s_waitcnt vmcnt(5)
	ds_write_b128 v152, v[38:41] offset:48192
	s_waitcnt lgkmcnt(0)
	s_barrier
	s_waitcnt vmcnt(0)
	ds_write_b128 v154, v[42:45]
	ds_write_b128 v155, v[6:9]
	ds_write_b128 v156, v[10:13]
	v_mov_b32_e32 v4, v1
	v_mov_b32_e32 v5, v1
	ds_write2_b64 v172, v[14:15], v[16:17] offset1:2
	ds_write2_b64 v173, v[18:19], v[20:21] offset1:2
	v_mov_b32_e32 v2, v1
	v_mov_b32_e32 v3, v1
	v_mov_b64_e32 v[8:9], v[4:5]
	v_mov_b64_e32 v[12:13], v[4:5]
	v_mov_b64_e32 v[16:17], v[4:5]
	v_mov_b64_e32 v[20:21], v[4:5]
	v_mov_b64_e32 v[24:25], v[4:5]
	v_mov_b64_e32 v[28:29], v[4:5]
	v_mov_b64_e32 v[32:33], v[4:5]
	v_mov_b64_e32 v[6:7], v[2:3]
	v_mov_b64_e32 v[10:11], v[2:3]
	v_mov_b64_e32 v[14:15], v[2:3]
	v_mov_b64_e32 v[18:19], v[2:3]
	v_mov_b64_e32 v[22:23], v[2:3]
	v_mov_b64_e32 v[26:27], v[2:3]
	v_mov_b64_e32 v[30:31], v[2:3]
	s_waitcnt lgkmcnt(0)
	s_barrier
	s_branch .LBB0_561
; __device__ __forceinline__ unsigned pack2(float lo, float hi) { unsigned r; asm("v_cvt_pk_bf16_f32 %0, %1, %2" : "=v"(r) : "v"(lo), "v"(hi)); return r; }
; __device__ __forceinline__ f32x4 mfma16(bf16x8 a, bf16x8 b, f32x4 c) { return __builtin_amdgcn_mfma_f32_16x16x32_bf16(a, b, c, 0, 0, 0); }
; __device__ __forceinline__ float fexp2(float x) { return __builtin_amdgcn_exp2f(x); }
; #define ATT_SCHED_BARRIER __builtin_amdgcn_sched_barrier(0)
; template <int DQK, int DV, int MODE> ...
;     ...
;           {
;             const float alpha = fexp2(mrow[qi] - mn);
;             lrow[qi] *= alpha;
; #pragma unroll
;             for (int dt = 0; dt < NDT; ++dt) O[qi][dt] *= alpha;
;           }
;           mrow[qi] = mn;
;           f32x4 ls4 = (f32x4){0.f, 0.f, 0.f, 0.f};
; #pragma unroll
;           for (int t = 0; t < 4; ++t) {
; #pragma unroll
;             for (int r = 0; r < 4; ++r) P[t][r] = fexp2(P[t][r]);
;             ls4 += P[t];
;           }
;           lrow[qi] += (ls4[0] + ls4[1]) + (ls4[2] + ls4[3]);
; #pragma unroll
;           for (int s2 = 0; s2 < 2; ++s2) {
;             u32x4 pk;
;             pk.x = pack2(P[2 * s2][0], P[2 * s2][1]); pk.y = pack2(P[2 * s2][2], P[2 * s2][3]);
;             pk.z = pack2(P[2 * s2 + 1][0], P[2 * s2 + 1][1]); pk.w = pack2(P[2 * s2 + 1][2], P[2 * s2 + 1][3]);
;             pf[qq][s2] = __builtin_bit_cast(bf16x8, pk);
;           }
;           ATT_SCHED_BARRIER;
;         }
; #pragma unroll
;         for (int s2 = 0; s2 < 2; ++s2)
; #pragma unroll
;           for (int dt = 0; dt < NDT; ++dt) {
;             const bf16x8 vf = *(const bf16x8*)(Vt + (dt * 16 + fr) * VTS + s2 * 32 + fq * 8);
; #pragma unroll
;             for (int qq = 0; qq < QG; ++qq) O[q0 + qq][dt] = mfma16(vf, pf[qq][s2], O[q0 + qq][dt]);
;             if ((dt & (ATT_PVB - 1)) == (ATT_PVB - 1)) ATT_SCHED_BARRIER;
;           }
.LBB0_559:
	s_or_b64 exec, exec, s[4:5]
	v_sub_f32_e32 v54, v169, v107
	v_cmp_neq_f32_e32 vcc, v169, v107
	v_exp_f32_e32 v54, v54
	v_pk_add_f32 v[56:57], v[82:83], v[116:117]
	v_pk_add_f32 v[58:59], v[114:115], v[112:113]
	v_pk_add_f32 v[56:57], v[110:111], v[56:57]
	v_pk_add_f32 v[58:59], v[80:81], v[58:59]
	v_pk_add_f32 v[56:57], v[78:79], v[56:57]
	v_pk_add_f32 v[58:59], v[84:85], v[58:59]
	s_cbranch_vccz .Lc_skip_r1
	v_pk_mul_f32 v[32:33], v[32:33], v[54:55] op_sel_hi:[1,0]
	v_pk_mul_f32 v[30:31], v[30:31], v[54:55] op_sel_hi:[1,0]
	v_pk_mul_f32 v[28:29], v[28:29], v[54:55] op_sel_hi:[1,0]
	v_pk_mul_f32 v[26:27], v[26:27], v[54:55] op_sel_hi:[1,0]
	v_pk_mul_f32 v[24:25], v[24:25], v[54:55] op_sel_hi:[1,0]
	v_pk_mul_f32 v[22:23], v[22:23], v[54:55] op_sel_hi:[1,0]
	v_pk_mul_f32 v[20:21], v[20:21], v[54:55] op_sel_hi:[1,0]
	v_pk_mul_f32 v[18:19], v[18:19], v[54:55] op_sel_hi:[1,0]
.Lc_skip_r1:
	v_add_f32_e32 v55, v56, v57
	v_add_f32_e32 v57, v58, v59
	v_add_f32_e32 v110, v55, v57
	v_fmac_f32_e32 v110, v168, v54
	v_exp_f32_e32 v54, v150
	v_exp_f32_e32 v55, v151
	v_exp_f32_e32 v58, v148
	v_exp_f32_e32 v59, v149
	v_exp_f32_e32 v60, v146
	v_exp_f32_e32 v62, v144
	v_exp_f32_e32 v63, v145
	v_exp_f32_e32 v61, v147
	v_exp_f32_e32 v76, v142
	v_exp_f32_e32 v77, v143
	v_exp_f32_e32 v78, v140
	v_exp_f32_e32 v79, v141
	v_exp_f32_e32 v80, v120
	v_exp_f32_e32 v82, v118
	v_exp_f32_e32 v83, v119
	v_exp_f32_e32 v81, v121
	v_sub_f32_e32 v56, v166, v109
	v_cmp_neq_f32_e32 vcc, v166, v109
	v_exp_f32_e32 v56, v56
	v_pk_add_f32 v[64:65], v[60:61], v[54:55]
	v_pk_add_f32 v[74:75], v[62:63], v[58:59]
	v_pk_add_f32 v[64:65], v[76:77], v[64:65]
	v_pk_add_f32 v[74:75], v[78:79], v[74:75]
	v_pk_add_f32 v[64:65], v[80:81], v[64:65]
	v_pk_add_f32 v[74:75], v[82:83], v[74:75]
	s_cbranch_vccz .Lc_skip_r2
	v_pk_mul_f32 v[16:17], v[16:17], v[56:57] op_sel_hi:[1,0]
	v_pk_mul_f32 v[14:15], v[14:15], v[56:57] op_sel_hi:[1,0]
	v_pk_mul_f32 v[12:13], v[12:13], v[56:57] op_sel_hi:[1,0]
	v_pk_mul_f32 v[10:11], v[10:11], v[56:57] op_sel_hi:[1,0]
	v_pk_mul_f32 v[8:9], v[8:9], v[56:57] op_sel_hi:[1,0]
	v_pk_mul_f32 v[6:7], v[6:7], v[56:57] op_sel_hi:[1,0]
	v_pk_mul_f32 v[4:5], v[4:5], v[56:57] op_sel_hi:[1,0]
	v_pk_mul_f32 v[2:3], v[2:3], v[56:57] op_sel_hi:[1,0]
.Lc_skip_r2:
	v_add_f32_e32 v64, v64, v65
	v_add_f32_e32 v65, v74, v75
	v_add_f32_e32 v74, v64, v65
	v_fmac_f32_e32 v74, v165, v56
	v_cvt_pk_bf16_f32 v54, v54, v55
	v_cvt_pk_bf16_f32 v55, v58, v59
	v_cvt_pk_bf16_f32 v56, v60, v61
	v_cvt_pk_bf16_f32 v57, v62, v63
	v_cvt_pk_bf16_f32 v58, v76, v77
	v_cvt_pk_bf16_f32 v59, v78, v79
	v_cvt_pk_bf16_f32 v60, v80, v81
	v_cvt_pk_bf16_f32 v61, v82, v83
	ds_read_b128 v[62:65], v208 offset:14336
	s_waitcnt lgkmcnt(0)
	v_mfma_f32_16x16x32_bf16 v[30:33], v[62:65], v[70:73], v[30:33]
	v_mfma_f32_16x16x32_bf16 v[14:17], v[62:65], v[54:57], v[14:17]
	ds_read_b128 v[62:65], v161 offset:14336
	s_waitcnt lgkmcnt(0)
	v_mfma_f32_16x16x32_bf16 v[26:29], v[62:65], v[70:73], v[26:29]
	v_mfma_f32_16x16x32_bf16 v[10:13], v[62:65], v[54:57], v[10:13]
	ds_read_b128 v[62:65], v207 offset:19456
	s_waitcnt lgkmcnt(0)
	v_mfma_f32_16x16x32_bf16 v[22:25], v[62:65], v[70:73], v[22:25]
	v_mfma_f32_16x16x32_bf16 v[6:9], v[62:65], v[54:57], v[6:9]
	ds_read_b128 v[62:65], v207 offset:22016
	s_waitcnt lgkmcnt(0)
	v_mfma_f32_16x16x32_bf16 v[18:21], v[62:65], v[70:73], v[18:21]
	v_mfma_f32_16x16x32_bf16 v[2:5], v[62:65], v[54:57], v[2:5]
	ds_read_b128 v[54:57], v208 offset:14400
	s_waitcnt lgkmcnt(0)
	v_mfma_f32_16x16x32_bf16 v[30:33], v[54:57], v[66:69], v[30:33]
	v_mfma_f32_16x16x32_bf16 v[14:17], v[54:57], v[58:61], v[14:17]
	ds_read_b128 v[54:57], v161 offset:14400
	s_waitcnt lgkmcnt(0)
	v_mfma_f32_16x16x32_bf16 v[26:29], v[54:57], v[66:69], v[26:29]
	v_mfma_f32_16x16x32_bf16 v[10:13], v[54:57], v[58:61], v[10:13]
	ds_read_b128 v[54:57], v207 offset:19520
	s_waitcnt lgkmcnt(0)
	v_mfma_f32_16x16x32_bf16 v[22:25], v[54:57], v[66:69], v[22:25]
	v_mfma_f32_16x16x32_bf16 v[6:9], v[54:57], v[58:61], v[6:9]
	ds_read_b128 v[54:57], v207 offset:22080
	s_waitcnt lgkmcnt(0)
	v_mfma_f32_16x16x32_bf16 v[18:21], v[54:57], v[66:69], v[18:21]
	v_mfma_f32_16x16x32_bf16 v[2:5], v[54:57], v[58:61], v[2:5]
	v_mov_b32_e32 v169, v107
	v_mov_b32_e32 v166, v109
	v_mov_b32_e32 v168, v110
	v_mov_b32_e32 v165, v74

; template <int DQK, int DV, int MODE> ...
;     ...
;   for (int kt = kt_begin; kt < kt_end; ++kt) {
;     const bool more = kt + 1 < kt_end;
;     if (more) gload(kt + 1);
;     ATT_SCHED_BARRIER;
;     bf16_t* Qs2 = Qs; asm volatile("" : "+v"(Qs2));
;     if (kt >= wkb && kt < wke) {
;       int path = 1; float cb = 0.f; bool need_mask = true;
;       if (MODE == 2) { need_mask = (kt * 64 + 63) > (qpos0 + w * 32); path = need_mask ? 1 : 0; }
;       if (MODE == 1) {
;         need_mask = (kt * 64 + 63) > (qpos0 + w * 32);
;         const int dmin = (qpos0 + w * 32) - (kt * 64 + 63);
;         if (dmin >= 0) {
;           const float blo = bias_lds[min(dmin, 2047)], bhi = bias_lds[min(dmin + 94, 2047)];
;           if (((__float_as_uint(blo) ^ __float_as_uint(bhi)) & 31u) == 0u) { path = 0; cb = blo; }
;         }
;       }
;       constexpr int QG = (DV == 128) ? ATT_QG_B : 2;
; #pragma unroll
;       for (int q0 = 0; q0 < 2; q0 += QG) {
;         f32x4 S[QG][4];
; #pragma unroll
;         for (int t = 0; t < 4; ++t) {
;           {
;             const bf16x8 kf = *(const bf16x8*)(Ks + (t * 16 + fr) * KST + fq * 8);
; #pragma unroll
;             for (int qq = 0; qq < QG; ++qq) S[qq][t] = __builtin_amdgcn_mfma_f32_16x16x32_bf16(kf, *(const bf16x8*)(Qs2 + ((q0 + qq) * NKS) * 512), (f32x4){0.f, 0.f, 0.f, 0.f}, 0, 0, 0);
;           }
; #pragma unroll
;           for (int ks = 1; ks < NKS; ++ks) {
;             const bf16x8 kf = *(const bf16x8*)(Ks + (t * 16 + fr) * KST + ks * 32 + fq * 8);
; #pragma unroll
;             for (int qq = 0; qq < QG; ++qq) S[qq][t] = mfma16(kf, *(const bf16x8*)(Qs2 + ((q0 + qq) * NKS + ks) * 512), S[qq][t]);
;           }
;         }
;         ATT_SCHED_BARRIER;
;         bf16x8 pf[QG][2];
; #pragma unroll
;         for (int qq = 0; qq < QG; ++qq) {
;           const int qi = q0 + qq;
;           const int qrow = w * 32 + qi * 16 + fr;
;           f32x4 P[4];
;           float mn;
;           if (path == 0) {
;             float mx = fmax3(S[qq][0][0], S[qq][0][1], S[qq][0][2]);
;             mx = fmax3(mx, S[qq][0][3], S[qq][1][0]); mx = fmax3(mx, S[qq][1][1], S[qq][1][2]); mx = fmax3(mx, S[qq][1][3], S[qq][2][0]);
;             mx = fmax3(mx, S[qq][2][1], S[qq][2][2]); mx = fmax3(mx, S[qq][2][3], S[qq][3][0]); mx = fmax3(mx, S[qq][3][1], S[qq][3][2]);
;             mx = fmax3(mx, S[qq][3][3], mx);
;             mx = xmax_rows(mx);
.LBB0_561:
	v_mov_b32_e32 v107, v1
	v_mov_b32_e32 v109, v1
	v_add3_u32 v46, v136, s15, 1
	v_mov_b32_e32 v47, v1
	v_add3_u32 v48, v138, s15, 1
	v_mov_b32_e32 v49, v1
	v_lshl_add_u64 v[34:35], v[0:1], 1, s[0:1]
	v_lshl_add_u64 v[38:39], v[106:107], 1, s[0:1]
	v_lshl_add_u64 v[42:43], v[108:109], 1, s[0:1]
	v_lshl_add_u64 v[46:47], v[46:47], 1, s[2:3]
	v_lshl_add_u64 v[48:49], v[48:49], 1, s[2:3]
	global_load_dwordx4 v[34:37], v[34:35], off
	s_nop 0
	global_load_dwordx4 v[38:41], v[38:39], off
	s_nop 0
	global_load_dwordx4 v[42:45], v[42:43], off
	s_nop 0
	global_load_dwordx4 v[50:53], v[46:47], off
	s_nop 0
	global_load_dwordx4 v[46:49], v[48:49], off
	v_mov_b64_e32 v[54:55], v[86:87]
	v_cmp_le_i32_e32 vcc, s17, v171
	s_and_saveexec_b64 s[12:13], vcc
	s_cbranch_execz .LBB0_560
	ds_read_b128 v[56:59], v54
	ds_read_b128 v[114:117], v54 offset:1024
	ds_read_b128 v[68:71], v54 offset:3072
	ds_read_b128 v[144:147], v54 offset:2048
	ds_read_b128 v[60:63], v157
	ds_read_b128 v[140:143], v157 offset:64
	ds_read_b128 v[72:75], v158
	ds_read_b128 v[80:83], v159
	ds_read_b128 v[118:121], v160
	v_add_co_u32_e32 v148, vcc, 0x1000, v54
	s_waitcnt lgkmcnt(0)
	v_mfma_f32_16x16x32_bf16 v[64:67], v[60:63], v[56:59], 0
	v_addc_co_u32_e32 v149, vcc, 0, v55, vcc
	v_cmp_le_i32_e32 vcc, s15, v170
	v_mfma_f32_16x16x32_bf16 v[60:63], v[60:63], v[68:71], 0
	v_mfma_f32_16x16x32_bf16 v[76:79], v[72:75], v[56:59], 0
	v_mfma_f32_16x16x32_bf16 v[72:75], v[72:75], v[68:71], 0
	v_mfma_f32_16x16x32_bf16 v[110:113], v[80:83], v[56:59], 0
	v_mfma_f32_16x16x32_bf16 v[80:83], v[80:83], v[68:71], 0
	v_mfma_f32_16x16x32_bf16 v[56:59], v[118:121], v[56:59], 0
	v_mfma_f32_16x16x32_bf16 v[68:71], v[118:121], v[68:71], 0
	ds_read_b128 v[118:121], v148
	s_nop 0
	ds_read_b128 v[148:151], v148 offset:1024
	v_mfma_f32_16x16x32_bf16 v[64:67], v[140:143], v[114:117], v[64:67]
	s_waitcnt lgkmcnt(0)
	v_mfma_f32_16x16x32_bf16 v[60:63], v[140:143], v[118:121], v[60:63]
	ds_read_b128 v[140:143], v158 offset:64
	s_waitcnt lgkmcnt(0)
	v_mfma_f32_16x16x32_bf16 v[76:79], v[140:143], v[114:117], v[76:79]
	v_mfma_f32_16x16x32_bf16 v[140:143], v[140:143], v[118:121], v[72:75]
	s_nop 2
	ds_read_b128 v[72:75], v159 offset:64
	s_waitcnt lgkmcnt(0)
	v_mfma_f32_16x16x32_bf16 v[110:113], v[72:75], v[114:117], v[110:113]
	v_mfma_f32_16x16x32_bf16 v[82:85], v[72:75], v[118:121], v[80:83]
	ds_read_b128 v[72:75], v160 offset:64
	s_waitcnt lgkmcnt(0)
	v_mfma_f32_16x16x32_bf16 v[114:117], v[72:75], v[114:117], v[56:59]
	s_nop 2
	ds_read_b128 v[54:57], v157 offset:128
	v_mfma_f32_16x16x32_bf16 v[118:121], v[72:75], v[118:121], v[68:71]
	s_waitcnt lgkmcnt(0)
	v_mfma_f32_16x16x32_bf16 v[70:73], v[54:57], v[144:147], v[64:67]
	v_mfma_f32_16x16x32_bf16 v[58:61], v[54:57], v[148:151], v[60:63]
	ds_read_b128 v[54:57], v158 offset:128
	s_nop 1
	ds_read_b128 v[62:65], v159 offset:128
	s_waitcnt lgkmcnt(1)
	v_mfma_f32_16x16x32_bf16 v[66:69], v[54:57], v[144:147], v[76:79]
	s_nop 2
	ds_read_b128 v[74:77], v160 offset:128
	v_mfma_f32_16x16x32_bf16 v[54:57], v[54:57], v[148:151], v[140:143]
	s_waitcnt lgkmcnt(1)
	v_mfma_f32_16x16x32_bf16 v[78:81], v[62:65], v[144:147], v[110:113]
	v_mfma_f32_16x16x32_bf16 v[62:65], v[62:65], v[148:151], v[82:85]
	s_waitcnt lgkmcnt(0)
	v_mfma_f32_16x16x32_bf16 v[82:85], v[74:77], v[144:147], v[114:117]
	v_mfma_f32_16x16x32_bf16 v[74:77], v[74:77], v[148:151], v[118:121]
	s_and_saveexec_b64 s[4:5], vcc
	s_xor_b64 s[4:5], exec, s[4:5]
	s_cbranch_execz .LBB0_564
	v_max3_f32 v107, v70, v71, v72
	s_mov_b32 s6, 0x3e16c740
	v_max3_f32 v107, v107, v73, v66
	v_max3_f32 v107, v107, v67, v68
	v_max3_f32 v107, v107, v69, v78
	v_max3_f32 v107, v107, v79, v80
	v_max3_f32 v107, v107, v81, v82
	v_max3_f32 v107, v107, v83, v84
	v_max3_f32 v107, v107, v85, v107
	v_mov_b32_e32 v109, v107
	s_nop 1
	v_permlane16_swap_b32_e32 v107, v109
	v_max3_f32 v107, v107, v109, v109
	v_mov_b32_e32 v109, v107
	s_nop 1
	v_permlane32_swap_b32_e32 v107, v109
	v_max3_f32 v107, v107, v109, v109
	v_fma_f32 v107, v107, s6, 0
	v_max3_f32 v107, v169, v107, v169
	v_sub_f32_e32 v116, 0, v107
	v_pk_fma_f32 v[118:119], v[84:85], s[6:7], v[116:117] op_sel_hi:[1,0,0]
	v_pk_fma_f32 v[120:121], v[82:83], s[6:7], v[116:117] op_sel_hi:[1,0,0]
	v_pk_fma_f32 v[140:141], v[80:81], s[6:7], v[116:117] op_sel_hi:[1,0,0]
	v_pk_fma_f32 v[110:111], v[78:79], s[6:7], v[116:117] op_sel_hi:[1,0,0]
	v_pk_fma_f32 v[114:115], v[68:69], s[6:7], v[116:117] op_sel_hi:[1,0,0]
	v_pk_fma_f32 v[142:143], v[66:67], s[6:7], v[116:117] op_sel_hi:[1,0,0]
	v_pk_fma_f32 v[112:113], v[72:73], s[6:7], v[116:117] op_sel_hi:[1,0,0]
	v_pk_fma_f32 v[116:117], v[70:71], s[6:7], v[116:117] op_sel_hi:[1,0,0]

; __device__ __forceinline__ unsigned pack2(float lo, float hi) { unsigned r; asm("v_cvt_pk_bf16_f32 %0, %1, %2" : "=v"(r) : "v"(lo), "v"(hi)); return r; }
; __device__ __forceinline__ float fexp2(float x) { return __builtin_amdgcn_exp2f(x); }
; __device__ __forceinline__ float fmax3(float a, float b, float c) { float r; asm("v_max3_f32 %0, %1, %2, %3" : "=v"(r) : "v"(a), "v"(b), "v"(c)); return r; }
; template <int DQK, int DV, int MODE> ...
;     ...
;           if (path == 0) {
;             float mx = fmax3(S[qq][0][0], S[qq][0][1], S[qq][0][2]);
;             mx = fmax3(mx, S[qq][0][3], S[qq][1][0]); mx = fmax3(mx, S[qq][1][1], S[qq][1][2]); mx = fmax3(mx, S[qq][1][3], S[qq][2][0]);
;             mx = fmax3(mx, S[qq][2][1], S[qq][2][2]); mx = fmax3(mx, S[qq][2][3], S[qq][3][0]); mx = fmax3(mx, S[qq][3][1], S[qq][3][2]);
;             mx = fmax3(mx, S[qq][3][3], mx);
;             mx = xmax_rows(mx);
;             mn = fmax3(mrow[qi], mx * c1 + cb, mrow[qi]);
;             const float off = cb - mn;
; #pragma unroll
;             for (int t = 0; t < 4; ++t) P[t] = S[qq][t] * c1 + off;
;     ...
; #pragma unroll
;           for (int t = 0; t < 4; ++t) {
; #pragma unroll
;             for (int r = 0; r < 4; ++r) P[t][r] = fexp2(P[t][r]);
;             ls4 += P[t];
;           }
;           lrow[qi] += (ls4[0] + ls4[1]) + (ls4[2] + ls4[3]);
; #pragma unroll
;           for (int s2 = 0; s2 < 2; ++s2) {
;             u32x4 pk;
;             pk.x = pack2(P[2 * s2][0], P[2 * s2][1]); pk.y = pack2(P[2 * s2][2], P[2 * s2][3]);
;             pk.z = pack2(P[2 * s2 + 1][0], P[2 * s2 + 1][1]); pk.w = pack2(P[2 * s2 + 1][2], P[2 * s2 + 1][3]);
;             pf[qq][s2] = __builtin_bit_cast(bf16x8, pk);
;           }
.LBB0_566:
	s_or_b64 exec, exec, s[4:5]
	v_exp_f32_e32 v116, v116
	v_exp_f32_e32 v117, v117
	v_exp_f32_e32 v112, v112
	v_exp_f32_e32 v113, v113
	v_exp_f32_e32 v82, v142
	v_exp_f32_e32 v83, v143
	v_exp_f32_e32 v114, v114
	v_exp_f32_e32 v115, v115
	v_exp_f32_e32 v110, v110
	v_exp_f32_e32 v111, v111
	v_exp_f32_e32 v80, v140
	v_exp_f32_e32 v81, v141
	v_exp_f32_e32 v78, v120
	v_exp_f32_e32 v79, v121
	v_exp_f32_e32 v84, v118
	v_exp_f32_e32 v85, v119
	v_cvt_pk_bf16_f32 v70, v116, v117
	v_cvt_pk_bf16_f32 v71, v112, v113
	v_cvt_pk_bf16_f32 v72, v82, v83
	v_cvt_pk_bf16_f32 v73, v114, v115
	v_cvt_pk_bf16_f32 v66, v110, v111
	v_cvt_pk_bf16_f32 v67, v80, v81
	v_cvt_pk_bf16_f32 v68, v78, v79
	v_cvt_pk_bf16_f32 v69, v84, v85
	s_and_saveexec_b64 s[4:5], vcc
	s_xor_b64 s[4:5], exec, s[4:5]
	s_cbranch_execz .LBB0_568
	v_max3_f32 v109, v58, v59, v60
	s_mov_b32 s6, 0x3e16c740
	v_max3_f32 v109, v109, v61, v54
	v_max3_f32 v109, v109, v55, v56
	v_max3_f32 v109, v109, v57, v62
	v_max3_f32 v109, v109, v63, v64
	v_max3_f32 v109, v109, v65, v74
	v_max3_f32 v109, v109, v75, v76
	v_max3_f32 v109, v109, v77, v109
	v_mov_b32_e32 v118, v109
	s_nop 1
	v_permlane16_swap_b32_e32 v109, v118
	v_max3_f32 v109, v109, v118, v118
	v_mov_b32_e32 v118, v109
	s_nop 1
	v_permlane32_swap_b32_e32 v109, v118
	v_max3_f32 v109, v109, v118, v118
	v_fma_f32 v109, v109, s6, 0
	v_max3_f32 v109, v166, v109, v166
	v_sub_f32_e32 v150, 0, v109
	v_pk_fma_f32 v[118:119], v[76:77], s[6:7], v[150:151] op_sel_hi:[1,0,0]
	v_pk_fma_f32 v[120:121], v[74:75], s[6:7], v[150:151] op_sel_hi:[1,0,0]
	v_pk_fma_f32 v[140:141], v[64:65], s[6:7], v[150:151] op_sel_hi:[1,0,0]
	v_pk_fma_f32 v[142:143], v[62:63], s[6:7], v[150:151] op_sel_hi:[1,0,0]
	v_pk_fma_f32 v[144:145], v[56:57], s[6:7], v[150:151] op_sel_hi:[1,0,0]
	v_pk_fma_f32 v[146:147], v[54:55], s[6:7], v[150:151] op_sel_hi:[1,0,0]
	v_pk_fma_f32 v[148:149], v[60:61], s[6:7], v[150:151] op_sel_hi:[1,0,0]
	v_pk_fma_f32 v[150:151], v[58:59], s[6:7], v[150:151] op_sel_hi:[1,0,0]
